# in-proj unit deal: k column tiles moved to the odd XCDs in exchange for four u tiles, to even out epilogue work between even and odd XCDs
# speedup vs baseline: 1.0068x; 1.0018x over previous
.LBB0_176:
	s_cmp_lt_i32 s26, 3
	s_cselect_b64 s[6:7], -1, 0
	s_and_b64 s[10:11], s[6:7], s[4:5]
	s_andn2_b64 vcc, exec, s[10:11]
	s_cbranch_vccnz .LBB0_291
	s_cmpk_lt_i32 s2, 0x300
	s_cselect_b64 s[4:5], -1, 0
	s_cmpk_gt_i32 s2, 0x2ff
	s_mov_b64 s[12:13], s[24:25]
	v_readfirstlane_b32 s22, v0
	s_cbranch_scc1 .LBB0_179
	s_ashr_i32 s6, s2, 31
	s_lshr_b32 s6, s6, 29
	s_add_i32 s6, s2, s6
	s_ashr_i32 s7, s6, 3
	s_and_b32 s6, s6, -8
	s_sub_i32 s6, s2, s6
	s_cmp_lt_i32 s6, 0
	s_movk_i32 s8, 0x61
	s_cselect_b32 s8, s8, 0x60
	s_mul_i32 s6, s6, s8
	s_add_i32 s6, s6, s7
	s_mul_hi_i32 s7, s6, 0x2aaaaaab
	s_lshr_b32 s8, s7, 31
	s_ashr_i32 s7, s7, 5
	s_add_i32 s7, s7, s8
	s_lshl_b32 s8, s7, 3
	s_mulk_i32 s7, 0xc0
	s_sub_i32 s7, s6, s7
	s_sext_i32_i16 s6, s7
	s_bfe_u32 s6, s6, 0x3001c
	s_add_i32 s6, s7, s6
	s_sext_i32_i16 s9, s6
	s_and_b32 s6, s6, 0xfff8
	s_sub_i32 s6, s7, s6
	s_sext_i32_i16 s6, s6
	s_add_i32 s6, s8, s6
	s_ashr_i32 s8, s9, 3
	s_add_i32 s9, s8, 4
	s_cmpk_gt_i32 s7, 0x5f
	s_cselect_b32 s62, s9, s8
	s_add_i32 s7, s62, 12
	s_sub_i32 s8, s62, 12
	s_sub_i32 s9, s62, 4
	s_cmp_lt_u32 s9, 4
	s_cselect_b32 s7, s7, s62
	s_sub_i32 s9, s62, 16
	s_cmp_lt_u32 s9, 4
	s_cselect_b32 s62, s8, s7

.LBB0_185:
	s_add_i32 s83, s83, 1
	s_mul_i32 s4, s83, s84
	s_mul_hi_u32 s5, s83, s3
	s_add_i32 s5, s5, s4
	s_mul_i32 s4, s83, s3
	s_add_u32 s58, s4, s2
	s_addc_u32 s59, s5, s85
	v_mov_b64_e32 v[2:3], 0x300
	v_cmp_lt_i64_e64 s[4:5], s[58:59], v[2:3]
	v_mov_b64_e32 v[2:3], 0x2ff
	v_cmp_gt_i64_e32 vcc, s[58:59], v[2:3]
	s_cbranch_vccnz .LBB0_187
	s_ashr_i32 s7, s58, 31
	s_lshr_b32 s7, s7, 29
	s_add_i32 s7, s58, s7
	s_ashr_i32 s54, s7, 3
	s_and_b32 s7, s7, -8
	s_sub_i32 s7, s58, s7
	s_cmp_lt_i32 s7, 0
	s_cselect_b32 s55, s88, 0x60
	s_mul_i32 s7, s7, s55
	s_add_i32 s7, s7, s54
	s_mul_hi_i32 s54, s7, 0x2aaaaaab
	s_lshr_b32 s55, s54, 31
	s_ashr_i32 s54, s54, 5
	s_add_i32 s54, s54, s55
	s_lshl_b32 s55, s54, 3
	s_sub_i32 s56, 32, s55
	s_min_i32 s56, s56, 8
	s_abs_i32 s57, s56
	v_cvt_f32_u32_e32 v2, s57
	s_sub_i32 s59, 0, s57
	s_mulk_i32 s54, 0xc0
	s_sub_i32 s7, s7, s54
	v_rcp_iflag_f32_e32 v2, v2
	s_abs_i32 s54, s7
	s_xor_b32 s58, s7, s56
	s_ashr_i32 s58, s58, 31
	v_mul_f32_e32 v2, 0x4f7ffffe, v2
	v_cvt_u32_f32_e32 v2, v2
	s_nop 0
	v_readfirstlane_b32 s60, v2
	s_mul_i32 s59, s59, s60
	s_mul_hi_u32 s59, s60, s59
	s_add_i32 s60, s60, s59
	s_mul_hi_u32 s59, s54, s60
	s_mul_i32 s60, s59, s57
	s_sub_i32 s54, s54, s60
	s_add_i32 s61, s59, 1
	s_sub_i32 s60, s54, s57
	s_cmp_ge_u32 s54, s57
	s_cselect_b32 s59, s61, s59
	s_cselect_b32 s54, s60, s54
	s_add_i32 s60, s59, 1
	s_cmp_ge_u32 s54, s57
	s_cselect_b32 s54, s60, s59
	s_xor_b32 s54, s54, s58
	s_sub_i32 s57, s54, s58
	s_mul_i32 s54, s57, s56
	s_sub_i32 s7, s7, s54
	s_add_i32 s54, s55, s7
	s_add_i32 s7, s57, 4
	s_cmp_gt_i32 s57, 11
	s_cselect_b32 s56, s7, s57
	s_add_i32 s57, s56, 12
	s_sub_i32 s58, s56, 12
	s_sub_i32 s59, s56, 4
	s_cmp_lt_u32 s59, 4
	s_cselect_b32 s57, s57, s56
	s_sub_i32 s59, s56, 16
	s_cmp_lt_u32 s59, 4
	s_cselect_b32 s56, s58, s57
